# tile scheduler arithmetic at each unit start specialised for the fixed 256-workgroup launch (18 scalar ops instead of a generic division sequence)
# speedup vs baseline: 1.0040x; 1.0040x over previous
.Lnr_p1:
	s_add_i32 s82, s82, 1
	v_readlane_b32 s0, v250, 2
	s_lshl_b32 s1, s82, 8
	s_add_i32 s1, s1, s0
	s_cmp_lt_u32 s1, 0x780
	s_cselect_b64 s[40:41], -1, 0
	s_lshl_b32 s1, s82, 5
	s_lshr_b32 s6, s0, 3
	s_add_i32 s1, s1, s6
	s_and_b32 s0, s0, 7
	s_lshl_b32 s0, s0, 3
	s_cmp_ge_u32 s1, 0x78
	s_cselect_b32 s6, 0x78, 0
	s_cselect_b32 s85, 4, 0
	s_sub_i32 s1, s1, s6
	s_add_i32 s85, s85, s0
	s_and_b32 s0, s1, 3
	s_add_i32 s85, s85, s0
	s_lshr_b32 s84, s1, 2

.Lnr_p4:
	s_add_i32 s90, s90, 1
	v_readlane_b32 s6, v250, 2
	s_lshl_b32 s7, s90, 8
	s_add_i32 s7, s7, s6
	s_cmp_lt_u32 s7, 0x200
	s_cselect_b64 s[40:41], -1, 0
	s_lshl_b32 s7, s90, 5
	s_lshr_b32 s10, s6, 3
	s_add_i32 s7, s7, s10
	s_and_b32 s6, s6, 7
	s_lshl_b32 s6, s6, 3
	s_cmp_ge_u32 s7, 0x20
	s_cselect_b32 s10, 0x20, 0
	s_cselect_b32 s92, 0, 4
	s_sub_i32 s7, s7, s10
	s_add_i32 s92, s92, s6
	s_and_b32 s6, s7, 3
	s_add_i32 s92, s92, s6
	s_lshr_b32 s93, s7, 2

.Lnr_p5:
	s_add_i32 s43, s43, 1
	v_readlane_b32 s4, v250, 2
	s_lshl_b32 s5, s43, 8
	s_add_i32 s5, s5, s4
	s_cmp_lt_u32 s5, 0xb00
	s_cselect_b64 s[38:39], -1, 0
	s_lshl_b32 s5, s43, 5
	s_lshr_b32 s48, s4, 3
	s_add_i32 s5, s5, s48
	s_and_b32 s4, s4, 7
	s_lshl_b32 s4, s4, 3
	s_cmp_ge_u32 s5, 0xb0
	s_cselect_b32 s48, 0xb0, 0
	s_cselect_b32 s45, 4, 0
	s_sub_i32 s5, s5, s48
	s_add_i32 s45, s45, s4
	s_and_b32 s4, s5, 3
	s_add_i32 s45, s45, s4
	s_lshr_b32 s44, s5, 2

.Lnr_p6:
	s_add_i32 s88, s88, 1
	v_readlane_b32 s6, v250, 2
	s_lshl_b32 s7, s88, 8
	s_add_i32 s7, s7, s6
	s_cmp_lt_u32 s7, 0x200
	s_cselect_b64 s[38:39], -1, 0
	s_lshl_b32 s7, s88, 5
	s_lshr_b32 s10, s6, 3
	s_add_i32 s7, s7, s10
	s_and_b32 s6, s6, 7
	s_lshl_b32 s6, s6, 3
	s_cmp_ge_u32 s7, 0x20
	s_cselect_b32 s10, 0x20, 0
	s_cselect_b32 s90, 0, 4
	s_sub_i32 s7, s7, s10
	s_add_i32 s90, s90, s6
	s_and_b32 s6, s7, 3
	s_add_i32 s90, s90, s6
	s_lshr_b32 s91, s7, 2
